# hand-written attention phase: ping-pong wave groups (2 barriers per tile, groups staggered), triple-buffered K/V LDS staging, generic item loop
# speedup vs baseline: 1.0022x; 1.0022x over previous
.LBB0_316:
	s_barrier
	v_readlane_b32 s4, v251, 48
	v_readlane_b32 s34, v253, 15
	v_mbcnt_lo_u32_b32 v0, -1, 0
	v_mbcnt_hi_u32_b32 v0, -1, v0
	s_lshr_b32 s36, s4, 2
	s_and_b32 s31, s4, 3
	s_lshr_b32 s29, s36, 3
	s_and_b32 s30, s36, 7
	s_lshr_b32 s34, s34, 6
	s_lshr_b32 s35, s34, 2
	v_and_b32_e32 v240, 31, v0
	v_lshrrev_b32_e32 v241, 5, v0
	v_lshl_add_u32 v247, s34, 6, v0
	v_lshrrev_b32_e32 v248, 4, v247
	v_and_b32_e32 v249, 15, v247
	v_lshlrev_b32_e32 v220, 11, v248
	v_lshl_add_u32 v220, v249, 4, v220
	v_mul_u32_u24_e32 v225, 0x190, v248
	v_lshl_add_u32 v225, v249, 4, v225
	v_lshrrev_b32_e32 v248, 3, v247
	v_and_b32_e32 v249, 7, v247
	v_lshlrev_b32_e32 v221, 7, v248
	v_lshl_add_u32 v221, v249, 4, v221
	v_mul_u32_u24_e32 v226, 0x190, v248
	v_lshl_add_u32 v226, v249, 4, v226
	v_add_u32_e32 v226, 0x100, v226
	v_mul_u32_u24_e32 v222, 0x8200, v248
	v_lshl_add_u32 v222, v249, 4, v222
	v_mul_u32_u24_e32 v227, 0x88, v248
	v_lshl_add_u32 v227, v249, 4, v227
	v_add_u32_e32 v227, 0x12c00, v227
	v_add_u32_e32 v228, 0x2200, v227
	v_lshlrev_b32_e32 v223, 5, v0
	v_lshlrev_b32_e32 v224, 2, v0
	v_add_u32_e32 v229, 0x1f800, v224
	v_mul_u32_u24_e32 v230, 0x190, v240
	v_lshl_add_u32 v230, v241, 4, v230
	v_mul_u32_u24_e32 v231, 0x88, v240
	v_lshl_add_u32 v231, v241, 3, v231
	v_add_u32_e32 v231, 0x12c00, v231
	v_lshlrev_b32_e32 v232, 4, v241
	v_add_u32_e32 v232, 0x1f800, v232
	v_xor_b32_e32 v233, 32, v0
	v_lshlrev_b32_e32 v233, 2, v233
	v_mov_b32_e32 v238, 0xf149f2ca
	s_mov_b32 s26, 0
.Lat_item:
	s_sub_i32 s36, 8, s31
	s_add_i32 s37, s31, 1
	s_cmp_eq_u32 s26, 0
	s_cselect_b32 s36, s36, s37
	s_cmp_eq_u32 s26, 2
	s_cselect_b32 s36, 0, s36
	s_lshl_b32 s27, s36, 8
	s_sub_i32 s27, s27, 0xf0
	s_cmp_eq_u32 s36, 0
	s_cselect_b32 s27, 0, s27
	s_cselect_b32 s28, 16, 0x100
	s_add_i32 s23, s27, s28
	s_add_i32 s23, s23, 63
	s_lshr_b32 s23, s23, 6
	s_lshl_b32 s65, s34, 5
	s_add_i32 s64, s65, s27
	s_add_i32 s25, s64, 31
	s_lshr_b32 s25, s25, 6
	s_cmp_lt_u32 s65, s28
	s_cselect_b32 s25, s25, -1
	s_mul_i32 s38, s29, 0x810
	v_add_u32_e32 v234, s64, v240
	v_lshlrev_b32_e32 v0, 2, v241
	v_sub_u32_e32 v239, v234, v0
	v_min_u32_e32 v0, 0x80f, v234
	v_add_u32_e32 v0, s38, v0
	s_movk_i32 s39, 0xc00
	v_mul_lo_u32 v247, v0, s39
	v_lshl_add_u32 v247, v241, 4, v247
	v_lshlrev_b32_e32 v242, 5, v0
	s_mul_i32 s36, s30, 0x180
	s_add_u32 s40, s50, s36
	s_addc_u32 s41, s51, 0
	global_load_dwordx4 v[98:101], v247, s[40:41]
	global_load_dwordx4 v[102:105], v247, s[40:41] offset:32
	global_load_dwordx4 v[106:109], v247, s[40:41] offset:64
	global_load_dwordx4 v[110:113], v247, s[40:41] offset:96
	global_load_dwordx4 v[114:117], v247, s[40:41] offset:128
	global_load_dwordx4 v[118:121], v247, s[40:41] offset:160
	global_load_dwordx4 v[122:125], v247, s[40:41] offset:192
	global_load_dwordx4 v[126:129], v247, s[40:41] offset:224
	global_load_dwordx4 v[130:133], v247, s[40:41] offset:256
	global_load_dwordx4 v[134:137], v247, s[40:41] offset:288
	global_load_dwordx4 v[138:141], v247, s[40:41] offset:320
	global_load_dwordx4 v[142:145], v247, s[40:41] offset:352
	s_lshl_b32 s36, s30, 2
	s_add_u32 s36, s36, 0x1507a400
	s_add_u32 s36, s48, s36
	s_addc_u32 s37, s49, 0
	global_load_dword v235, v242, s[36:37]
	s_lshl_b32 s73, s38, 11
	s_add_u32 s72, s73, 0x10480000
	s_lshl_b32 s73, s30, 8
	s_add_u32 s72, s72, s73
	s_add_u32 s8, s48, s72
	s_addc_u32 s9, s49, 0
	s_add_u32 s10, s8, 0x10000
	s_addc_u32 s11, s9, 0
	s_lshl_b32 s73, s38, 7
	s_add_u32 s72, s73, 0x14da0000
	s_add_u32 s12, s48, s72
	s_addc_u32 s13, s49, 0
	s_mul_i32 s73, s30, 0x410000
	s_lshl_b32 s72, s38, 1
	s_add_u32 s72, s72, s73
	s_add_u32 s72, s72, 0x12500000
	s_add_u32 s14, s48, s72
	s_addc_u32 s15, s49, 0
	s_add_u32 s16, s14, 0x208000
	s_addc_u32 s17, s15, 0
	s_lshl_b32 s73, s38, 5
	s_add_u32 s72, s73, 0x150fc400
	s_lshl_b32 s73, s30, 2
	s_add_u32 s72, s72, s73
	s_add_u32 s18, s48, s72
	s_addc_u32 s19, s49, 0
	s_lshl_b32 s73, s38, 2
	s_add_u32 s72, s73, 0x1506a000
	s_add_u32 s20, s48, s72
	s_addc_u32 s21, s49, 0
	v_mov_b32_e32 v2, 0
	v_mov_b32_e32 v3, 0
	v_mov_b32_e32 v4, 0
	v_mov_b32_e32 v5, 0
	v_mov_b32_e32 v6, 0
	v_mov_b32_e32 v7, 0
	v_mov_b32_e32 v8, 0
	v_mov_b32_e32 v9, 0
	v_mov_b32_e32 v10, 0
	v_mov_b32_e32 v11, 0
	v_mov_b32_e32 v12, 0
	v_mov_b32_e32 v13, 0
	v_mov_b32_e32 v14, 0
	v_mov_b32_e32 v15, 0
	v_mov_b32_e32 v16, 0
	v_mov_b32_e32 v17, 0
	v_mov_b32_e32 v18, 0
	v_mov_b32_e32 v19, 0
	v_mov_b32_e32 v20, 0
	v_mov_b32_e32 v21, 0
	v_mov_b32_e32 v22, 0
	v_mov_b32_e32 v23, 0
	v_mov_b32_e32 v24, 0
	v_mov_b32_e32 v25, 0
	v_mov_b32_e32 v26, 0
	v_mov_b32_e32 v27, 0
	v_mov_b32_e32 v28, 0
	v_mov_b32_e32 v29, 0
	v_mov_b32_e32 v30, 0
	v_mov_b32_e32 v31, 0
	v_mov_b32_e32 v32, 0
	v_mov_b32_e32 v33, 0
	v_mov_b32_e32 v34, 0
	v_mov_b32_e32 v35, 0
	v_mov_b32_e32 v36, 0
	v_mov_b32_e32 v37, 0
	v_mov_b32_e32 v38, 0
	v_mov_b32_e32 v39, 0
	v_mov_b32_e32 v40, 0
	v_mov_b32_e32 v41, 0
	v_mov_b32_e32 v42, 0
	v_mov_b32_e32 v43, 0
	v_mov_b32_e32 v44, 0
	v_mov_b32_e32 v45, 0
	v_mov_b32_e32 v46, 0
	v_mov_b32_e32 v47, 0
	v_mov_b32_e32 v48, 0
	v_mov_b32_e32 v49, 0
	v_mov_b32_e32 v50, 0
	v_mov_b32_e32 v51, 0
	v_mov_b32_e32 v52, 0
	v_mov_b32_e32 v53, 0
	v_mov_b32_e32 v54, 0
	v_mov_b32_e32 v55, 0
	v_mov_b32_e32 v56, 0
	v_mov_b32_e32 v57, 0
	v_mov_b32_e32 v58, 0
	v_mov_b32_e32 v59, 0
	v_mov_b32_e32 v60, 0
	v_mov_b32_e32 v61, 0
	v_mov_b32_e32 v62, 0
	v_mov_b32_e32 v63, 0
	v_mov_b32_e32 v64, 0
	v_mov_b32_e32 v65, 0
	v_mov_b32_e32 v236, v238
	v_mov_b32_e32 v237, 0
	global_load_dwordx4 v[198:201], v220, s[8:9]
	global_load_dwordx4 v[202:205], v220, s[10:11]
	global_load_dwordx4 v[206:209], v221, s[12:13]
	global_load_dwordx4 v[210:213], v222, s[14:15]
	global_load_dwordx4 v[214:217], v222, s[16:17]
	s_cmp_lg_u32 s34, 0
	s_cbranch_scc1 .Lat_nosq1
	global_load_dword v218, v223, s[18:19]
	global_load_dword v219, v224, s[20:21]
.Lat_nosq1:
	s_mov_b32 s36, 0
	s_mov_b32 s37, 0
	s_mov_b32 s39, 0
	s_waitcnt vmcnt(0)
	v_add_u32_e32 v0, s36, v225
	ds_write_b128 v0, v[198:201]
	ds_write_b128 v0, v[202:205] offset:12800
	v_add_u32_e32 v0, s36, v226
	ds_write_b128 v0, v[206:209]
	v_add_u32_e32 v0, s37, v227
	ds_write2_b64 v0, v[210:211], v[212:213] offset1:1
	v_add_u32_e32 v0, s37, v228
	ds_write2_b64 v0, v[214:215], v[216:217] offset1:1
	s_cmp_lg_u32 s34, 0
	s_cbranch_scc1 .Lat_nosc2
	v_add_f32_e32 v247, v218, v219
	v_mov_b32_e32 v242, 0x358637bd
	v_fmamk_f32 v247, v247, 0x3baaaaab, v242
	v_rsq_f32_e32 v247, v247
	v_add_u32_e32 v0, s39, v229
	s_nop 0
	ds_write_b32 v0, v247
.Lat_nosc2:
	v_mov_b32_e32 v242, 0x358637bd
	v_fmamk_f32 v235, v235, 0x3baaaaab, v242
	v_rsq_f32_e32 v235, v235
	s_nop 0
	v_mul_f32_e32 v235, 0x3dd53b95, v235
	s_cmp_lt_u32 s23, 2
	s_cbranch_scc1 .Lat_no_t1
	s_add_u32 s8, s8, 0x20000
	s_addc_u32 s9, s9, 0
	s_add_u32 s10, s10, 0x20000
	s_addc_u32 s11, s11, 0
	s_add_u32 s12, s12, 0x2000
	s_addc_u32 s13, s13, 0
	s_add_u32 s14, s14, 0x80
	s_addc_u32 s15, s15, 0
	s_add_u32 s16, s16, 0x80
	s_addc_u32 s17, s17, 0
	s_add_u32 s18, s18, 0x800
	s_addc_u32 s19, s19, 0
	s_add_u32 s20, s20, 0x100
	s_addc_u32 s21, s21, 0
	global_load_dwordx4 v[198:201], v220, s[8:9]
	global_load_dwordx4 v[202:205], v220, s[10:11]
	global_load_dwordx4 v[206:209], v221, s[12:13]
	global_load_dwordx4 v[210:213], v222, s[14:15]
	global_load_dwordx4 v[214:217], v222, s[16:17]
	s_cmp_lg_u32 s34, 0
	s_cbranch_scc1 .Lat_nosq3
	global_load_dword v218, v223, s[18:19]
	global_load_dword v219, v224, s[20:21]
.Lat_nosq3:
.Lat_no_t1:
	s_waitcnt lgkmcnt(0)
	s_barrier
	s_mov_b32 s22, 0
	s_mov_b32 s24, 0
	s_cmp_eq_u32 s35, 0
	s_cbranch_scc1 .Lat_loop
	s_barrier
.Lat_loop:
	s_add_i32 s65, s22, 1
	s_cmp_ge_u32 s65, s23
	s_cbranch_scc1 .Lat_x_nostore
	s_add_i32 s72, s24, 1
	s_cmp_eq_u32 s72, 3
	s_cselect_b32 s72, 0, s72
	s_mul_i32 s36, s72, 0x6400
	s_mul_i32 s37, s72, 0x4400
	s_lshl_b32 s39, s72, 8
	s_waitcnt vmcnt(0)
	v_add_u32_e32 v0, s36, v225
	ds_write_b128 v0, v[198:201]
	ds_write_b128 v0, v[202:205] offset:12800
	v_add_u32_e32 v0, s36, v226
	ds_write_b128 v0, v[206:209]
	v_add_u32_e32 v0, s37, v227
	ds_write2_b64 v0, v[210:211], v[212:213] offset1:1
	v_add_u32_e32 v0, s37, v228
	ds_write2_b64 v0, v[214:215], v[216:217] offset1:1
	s_cmp_lg_u32 s34, 0
	s_cbranch_scc1 .Lat_nosc4
	v_add_f32_e32 v247, v218, v219
	v_mov_b32_e32 v242, 0x358637bd
	v_fmamk_f32 v247, v247, 0x3baaaaab, v242
	v_rsq_f32_e32 v247, v247
	v_add_u32_e32 v0, s39, v229
	s_nop 0
	ds_write_b32 v0, v247
.Lat_nosc4:
	s_add_i32 s65, s22, 2
	s_cmp_ge_u32 s65, s23
	s_cbranch_scc1 .Lat_x_nostore
	s_add_u32 s8, s8, 0x20000
	s_addc_u32 s9, s9, 0
	s_add_u32 s10, s10, 0x20000
	s_addc_u32 s11, s11, 0
	s_add_u32 s12, s12, 0x2000
	s_addc_u32 s13, s13, 0
	s_add_u32 s14, s14, 0x80
	s_addc_u32 s15, s15, 0
	s_add_u32 s16, s16, 0x80
	s_addc_u32 s17, s17, 0
	s_add_u32 s18, s18, 0x800
	s_addc_u32 s19, s19, 0
	s_add_u32 s20, s20, 0x100
	s_addc_u32 s21, s21, 0
	global_load_dwordx4 v[198:201], v220, s[8:9]
	global_load_dwordx4 v[202:205], v220, s[10:11]
	global_load_dwordx4 v[206:209], v221, s[12:13]
	global_load_dwordx4 v[210:213], v222, s[14:15]
	global_load_dwordx4 v[214:217], v222, s[16:17]
	s_cmp_lg_u32 s34, 0
	s_cbranch_scc1 .Lat_nosq5
	global_load_dword v218, v223, s[18:19]
	global_load_dword v219, v224, s[20:21]
.Lat_nosq5:
.Lat_x_nostore:
	s_cmp_eq_u32 s22, 0
	s_cbranch_scc1 .Lat_x_nopv
	s_add_i32 s65, s22, -1
	s_cmp_gt_i32 s65, s25
	s_cbranch_scc1 .Lat_x_nopv
	s_add_i32 s72, s24, 2
	s_cmp_ge_u32 s72, 3
	s_cbranch_scc0 .Lat_x_pvb
	s_sub_i32 s72, s72, 3
.Lat_x_pvb:
	s_mul_i32 s37, s72, 0x4400
	v_add_u32_e32 v243, s37, v231
	v_add_u32_e32 v244, 0x1100, v243
	v_add_u32_e32 v245, 0x2200, v243
	v_add_u32_e32 v246, 0x3300, v243
	ds_read2_b64 v[186:189], v243 offset0:0 offset1:2
	ds_read2_b64 v[190:193], v244 offset0:0 offset1:2
	s_waitcnt lgkmcnt(1)
	v_mfma_f32_32x32x16_bf16 v[2:17], v[186:189], v[146:149], v[2:17]
	ds_read2_b64 v[194:197], v245 offset0:0 offset1:2
	s_waitcnt lgkmcnt(1)
	v_mfma_f32_32x32x16_bf16 v[18:33], v[190:193], v[146:149], v[18:33]
	ds_read2_b64 v[186:189], v246 offset0:0 offset1:2
	s_waitcnt lgkmcnt(1)
	v_mfma_f32_32x32x16_bf16 v[34:49], v[194:197], v[146:149], v[34:49]
	ds_read2_b64 v[190:193], v243 offset0:4 offset1:6
	s_waitcnt lgkmcnt(1)
	v_mfma_f32_32x32x16_bf16 v[50:65], v[186:189], v[146:149], v[50:65]
	ds_read2_b64 v[194:197], v244 offset0:4 offset1:6
	s_waitcnt lgkmcnt(1)
	v_mfma_f32_32x32x16_bf16 v[2:17], v[190:193], v[150:153], v[2:17]
	ds_read2_b64 v[186:189], v245 offset0:4 offset1:6
	s_waitcnt lgkmcnt(1)
	v_mfma_f32_32x32x16_bf16 v[18:33], v[194:197], v[150:153], v[18:33]
	ds_read2_b64 v[190:193], v246 offset0:4 offset1:6
	s_waitcnt lgkmcnt(1)
	v_mfma_f32_32x32x16_bf16 v[34:49], v[186:189], v[150:153], v[34:49]
	ds_read2_b64 v[194:197], v243 offset0:8 offset1:10
	s_waitcnt lgkmcnt(1)
	v_mfma_f32_32x32x16_bf16 v[50:65], v[190:193], v[150:153], v[50:65]
	ds_read2_b64 v[186:189], v244 offset0:8 offset1:10
	s_waitcnt lgkmcnt(1)
	v_mfma_f32_32x32x16_bf16 v[2:17], v[194:197], v[154:157], v[2:17]
	ds_read2_b64 v[190:193], v245 offset0:8 offset1:10
	s_waitcnt lgkmcnt(1)
	v_mfma_f32_32x32x16_bf16 v[18:33], v[186:189], v[154:157], v[18:33]
	ds_read2_b64 v[194:197], v246 offset0:8 offset1:10
	s_waitcnt lgkmcnt(1)
	v_mfma_f32_32x32x16_bf16 v[34:49], v[190:193], v[154:157], v[34:49]
	ds_read2_b64 v[186:189], v243 offset0:12 offset1:14
	s_waitcnt lgkmcnt(1)
	v_mfma_f32_32x32x16_bf16 v[50:65], v[194:197], v[154:157], v[50:65]
	ds_read2_b64 v[190:193], v244 offset0:12 offset1:14
	s_waitcnt lgkmcnt(1)
	v_mfma_f32_32x32x16_bf16 v[2:17], v[186:189], v[158:161], v[2:17]
	ds_read2_b64 v[194:197], v245 offset0:12 offset1:14
	s_waitcnt lgkmcnt(1)
	v_mfma_f32_32x32x16_bf16 v[18:33], v[190:193], v[158:161], v[18:33]
	ds_read2_b64 v[186:189], v246 offset0:12 offset1:14
	s_waitcnt lgkmcnt(1)
	v_mfma_f32_32x32x16_bf16 v[34:49], v[194:197], v[158:161], v[34:49]
	s_waitcnt lgkmcnt(0)
	v_mfma_f32_32x32x16_bf16 v[50:65], v[186:189], v[158:161], v[50:65]
.Lat_x_nopv:
	s_cmp_gt_i32 s22, s25
	s_cbranch_scc1 .Lat_x_noqk
	s_mul_i32 s36, s24, 0x6400
	v_add_u32_e32 v0, s36, v230
	ds_read_b128 v[162:165], v0
	ds_read_b128 v[166:169], v0 offset:12800
	ds_read_b128 v[170:173], v0 offset:32
	ds_read_b128 v[174:177], v0 offset:12832
	s_waitcnt lgkmcnt(2)
	v_mfma_f32_32x32x16_bf16 v[66:81], v[162:165], v[98:101], 0
	v_mfma_f32_32x32x16_bf16 v[82:97], v[166:169], v[98:101], 0
	ds_read_b128 v[178:181], v0 offset:64
	ds_read_b128 v[182:185], v0 offset:12864
	s_waitcnt lgkmcnt(2)
	v_mfma_f32_32x32x16_bf16 v[66:81], v[170:173], v[102:105], v[66:81]
	v_mfma_f32_32x32x16_bf16 v[82:97], v[174:177], v[102:105], v[82:97]
	ds_read_b128 v[162:165], v0 offset:96
	ds_read_b128 v[166:169], v0 offset:12896
	s_waitcnt lgkmcnt(2)
	v_mfma_f32_32x32x16_bf16 v[66:81], v[178:181], v[106:109], v[66:81]
	v_mfma_f32_32x32x16_bf16 v[82:97], v[182:185], v[106:109], v[82:97]
	ds_read_b128 v[170:173], v0 offset:128
	ds_read_b128 v[174:177], v0 offset:12928
	s_waitcnt lgkmcnt(2)
	v_mfma_f32_32x32x16_bf16 v[66:81], v[162:165], v[110:113], v[66:81]
	v_mfma_f32_32x32x16_bf16 v[82:97], v[166:169], v[110:113], v[82:97]
	ds_read_b128 v[178:181], v0 offset:160
	ds_read_b128 v[182:185], v0 offset:12960
	s_waitcnt lgkmcnt(2)
	v_mfma_f32_32x32x16_bf16 v[66:81], v[170:173], v[114:117], v[66:81]
	v_mfma_f32_32x32x16_bf16 v[82:97], v[174:177], v[114:117], v[82:97]
	ds_read_b128 v[162:165], v0 offset:192
	ds_read_b128 v[166:169], v0 offset:12992
	s_waitcnt lgkmcnt(2)
	v_mfma_f32_32x32x16_bf16 v[66:81], v[178:181], v[118:121], v[66:81]
	v_mfma_f32_32x32x16_bf16 v[82:97], v[182:185], v[118:121], v[82:97]
	ds_read_b128 v[170:173], v0 offset:224
	ds_read_b128 v[174:177], v0 offset:13024
	s_waitcnt lgkmcnt(2)
	v_mfma_f32_32x32x16_bf16 v[66:81], v[162:165], v[122:125], v[66:81]
	v_mfma_f32_32x32x16_bf16 v[82:97], v[166:169], v[122:125], v[82:97]
	ds_read_b128 v[178:181], v0 offset:256
	ds_read_b128 v[182:185], v0 offset:13056
	s_waitcnt lgkmcnt(2)
	v_mfma_f32_32x32x16_bf16 v[66:81], v[170:173], v[126:129], v[66:81]
	v_mfma_f32_32x32x16_bf16 v[82:97], v[174:177], v[126:129], v[82:97]
	ds_read_b128 v[162:165], v0 offset:288
	ds_read_b128 v[166:169], v0 offset:13088
	s_waitcnt lgkmcnt(2)
	v_mfma_f32_32x32x16_bf16 v[66:81], v[178:181], v[130:133], v[66:81]
	v_mfma_f32_32x32x16_bf16 v[82:97], v[182:185], v[130:133], v[82:97]
	ds_read_b128 v[170:173], v0 offset:320
	ds_read_b128 v[174:177], v0 offset:13120
	s_waitcnt lgkmcnt(2)
	v_mfma_f32_32x32x16_bf16 v[66:81], v[162:165], v[134:137], v[66:81]
	v_mfma_f32_32x32x16_bf16 v[82:97], v[166:169], v[134:137], v[82:97]
	ds_read_b128 v[178:181], v0 offset:352
	ds_read_b128 v[182:185], v0 offset:13152
	s_waitcnt lgkmcnt(2)
	v_mfma_f32_32x32x16_bf16 v[66:81], v[170:173], v[138:141], v[66:81]
	v_mfma_f32_32x32x16_bf16 v[82:97], v[174:177], v[138:141], v[82:97]
	s_waitcnt lgkmcnt(0)
	v_mfma_f32_32x32x16_bf16 v[66:81], v[178:181], v[142:145], v[66:81]
	v_mfma_f32_32x32x16_bf16 v[82:97], v[182:185], v[142:145], v[82:97]
	s_lshl_b32 s39, s24, 8
	v_add_u32_e32 v0, s39, v232
	ds_read_b128 v[162:165], v0
	ds_read_b128 v[166:169], v0 offset:32
	ds_read_b128 v[170:173], v0 offset:64
	ds_read_b128 v[174:177], v0 offset:96
	ds_read_b128 v[178:181], v0 offset:128
	ds_read_b128 v[182:185], v0 offset:160
	ds_read_b128 v[186:189], v0 offset:192
	ds_read_b128 v[190:193], v0 offset:224
	s_barrier
	s_nop 7
	s_waitcnt lgkmcnt(0)
	v_pk_mul_f32 v[66:67], v[66:67], v[162:163]
	v_pk_mul_f32 v[68:69], v[68:69], v[164:165]
	v_pk_mul_f32 v[70:71], v[70:71], v[166:167]
	v_pk_mul_f32 v[72:73], v[72:73], v[168:169]
	v_pk_mul_f32 v[74:75], v[74:75], v[170:171]
	v_pk_mul_f32 v[76:77], v[76:77], v[172:173]
	v_pk_mul_f32 v[78:79], v[78:79], v[174:175]
	v_pk_mul_f32 v[80:81], v[80:81], v[176:177]
	v_pk_mul_f32 v[82:83], v[82:83], v[178:179]
	v_pk_mul_f32 v[84:85], v[84:85], v[180:181]
	v_pk_mul_f32 v[86:87], v[86:87], v[182:183]
	v_pk_mul_f32 v[88:89], v[88:89], v[184:185]
	v_pk_mul_f32 v[90:91], v[90:91], v[186:187]
	v_pk_mul_f32 v[92:93], v[92:93], v[188:189]
	v_pk_mul_f32 v[94:95], v[94:95], v[190:191]
	v_pk_mul_f32 v[96:97], v[96:97], v[192:193]
	s_lshl_b32 s65, s22, 6
	s_add_i32 s72, s65, 63
	s_cmp_le_i32 s72, s64
	s_cbranch_scc1 .Lat_y_nomask
	v_subrev_u32_e32 v242, s65, v239
	v_cmp_gt_i32_e32 vcc, 0, v242
	v_cmp_gt_i32_e64 s[36:37], 1, v242
	s_nop 0
	v_cndmask_b32_e32 v66, v66, v238, vcc
	v_cndmask_b32_e64 v67, v67, v238, s[36:37]
	v_cmp_gt_i32_e32 vcc, 2, v242
	v_cmp_gt_i32_e64 s[36:37], 3, v242
	s_nop 0
	v_cndmask_b32_e32 v68, v68, v238, vcc
	v_cndmask_b32_e64 v69, v69, v238, s[36:37]
	v_cmp_gt_i32_e32 vcc, 8, v242
	v_cmp_gt_i32_e64 s[36:37], 9, v242
	s_nop 0
	v_cndmask_b32_e32 v70, v70, v238, vcc
	v_cndmask_b32_e64 v71, v71, v238, s[36:37]
	v_cmp_gt_i32_e32 vcc, 10, v242
	v_cmp_gt_i32_e64 s[36:37], 11, v242
	s_nop 0
	v_cndmask_b32_e32 v72, v72, v238, vcc
	v_cndmask_b32_e64 v73, v73, v238, s[36:37]
	v_cmp_gt_i32_e32 vcc, 16, v242
	v_cmp_gt_i32_e64 s[36:37], 17, v242
	s_nop 0
	v_cndmask_b32_e32 v74, v74, v238, vcc
	v_cndmask_b32_e64 v75, v75, v238, s[36:37]
	v_cmp_gt_i32_e32 vcc, 18, v242
	v_cmp_gt_i32_e64 s[36:37], 19, v242
	s_nop 0
	v_cndmask_b32_e32 v76, v76, v238, vcc
	v_cndmask_b32_e64 v77, v77, v238, s[36:37]
	v_cmp_gt_i32_e32 vcc, 24, v242
	v_cmp_gt_i32_e64 s[36:37], 25, v242
	s_nop 0
	v_cndmask_b32_e32 v78, v78, v238, vcc
	v_cndmask_b32_e64 v79, v79, v238, s[36:37]
	v_cmp_gt_i32_e32 vcc, 26, v242
	v_cmp_gt_i32_e64 s[36:37], 27, v242
	s_nop 0
	v_cndmask_b32_e32 v80, v80, v238, vcc
	v_cndmask_b32_e64 v81, v81, v238, s[36:37]
	v_cmp_gt_i32_e32 vcc, 32, v242
	v_cmp_gt_i32_e64 s[36:37], 33, v242
	s_nop 0
	v_cndmask_b32_e32 v82, v82, v238, vcc
	v_cndmask_b32_e64 v83, v83, v238, s[36:37]
	v_cmp_gt_i32_e32 vcc, 34, v242
	v_cmp_gt_i32_e64 s[36:37], 35, v242
	s_nop 0
	v_cndmask_b32_e32 v84, v84, v238, vcc
	v_cndmask_b32_e64 v85, v85, v238, s[36:37]
	v_cmp_gt_i32_e32 vcc, 40, v242
	v_cmp_gt_i32_e64 s[36:37], 41, v242
	s_nop 0
	v_cndmask_b32_e32 v86, v86, v238, vcc
	v_cndmask_b32_e64 v87, v87, v238, s[36:37]
	v_cmp_gt_i32_e32 vcc, 42, v242
	v_cmp_gt_i32_e64 s[36:37], 43, v242
	s_nop 0
	v_cndmask_b32_e32 v88, v88, v238, vcc
	v_cndmask_b32_e64 v89, v89, v238, s[36:37]
	v_cmp_gt_i32_e32 vcc, 48, v242
	v_cmp_gt_i32_e64 s[36:37], 49, v242
	s_nop 0
	v_cndmask_b32_e32 v90, v90, v238, vcc
	v_cndmask_b32_e64 v91, v91, v238, s[36:37]
	v_cmp_gt_i32_e32 vcc, 50, v242
	v_cmp_gt_i32_e64 s[36:37], 51, v242
	s_nop 0
	v_cndmask_b32_e32 v92, v92, v238, vcc
	v_cndmask_b32_e64 v93, v93, v238, s[36:37]
	v_cmp_gt_i32_e32 vcc, 56, v242
	v_cmp_gt_i32_e64 s[36:37], 57, v242
	s_nop 0
	v_cndmask_b32_e32 v94, v94, v238, vcc
	v_cndmask_b32_e64 v95, v95, v238, s[36:37]
	v_cmp_gt_i32_e32 vcc, 58, v242
	v_cmp_gt_i32_e64 s[36:37], 59, v242
	s_nop 0
	v_cndmask_b32_e32 v96, v96, v238, vcc
	v_cndmask_b32_e64 v97, v97, v238, s[36:37]
.Lat_y_nomask:
	v_max3_f32 v247, v66, v67, v68
	v_max3_f32 v0, v82, v83, v84
	v_max3_f32 v247, v247, v69, v70
	v_max3_f32 v0, v0, v85, v86
	v_max3_f32 v247, v247, v71, v72
	v_max3_f32 v0, v0, v87, v88
	v_max3_f32 v247, v247, v73, v74
	v_max3_f32 v0, v0, v89, v90
	v_max3_f32 v247, v247, v75, v76
	v_max3_f32 v0, v0, v91, v92
	v_max3_f32 v247, v247, v77, v78
	v_max3_f32 v0, v0, v93, v94
	v_max3_f32 v247, v247, v79, v80
	v_max3_f32 v0, v0, v95, v96
	v_max3_f32 v247, v247, v81, v97
	v_max_f32_e32 v247, v247, v0
	ds_bpermute_b32 v0, v233, v247
	s_waitcnt lgkmcnt(0)
	v_max_f32_e32 v247, v247, v0
	v_mul_f32_e32 v0, v235, v247
	v_sub_f32_e32 v194, v0, v236
	v_cmp_lt_f32_e32 vcc, 0x41000000, v194
	s_nop 1
	v_cndmask_b32_e32 v195, v236, v0, vcc
	v_sub_f32_e32 v248, v236, v195
	v_exp_f32_e32 v248, v248
	s_nop 0
	s_cbranch_vccz .Lat_y_norescale
	v_pk_mul_f32 v[2:3], v[2:3], v[248:249] op_sel_hi:[1,0]
	v_pk_mul_f32 v[4:5], v[4:5], v[248:249] op_sel_hi:[1,0]
	v_pk_mul_f32 v[6:7], v[6:7], v[248:249] op_sel_hi:[1,0]
	v_pk_mul_f32 v[8:9], v[8:9], v[248:249] op_sel_hi:[1,0]
	v_pk_mul_f32 v[10:11], v[10:11], v[248:249] op_sel_hi:[1,0]
	v_pk_mul_f32 v[12:13], v[12:13], v[248:249] op_sel_hi:[1,0]
	v_pk_mul_f32 v[14:15], v[14:15], v[248:249] op_sel_hi:[1,0]
	v_pk_mul_f32 v[16:17], v[16:17], v[248:249] op_sel_hi:[1,0]
	v_pk_mul_f32 v[18:19], v[18:19], v[248:249] op_sel_hi:[1,0]
	v_pk_mul_f32 v[20:21], v[20:21], v[248:249] op_sel_hi:[1,0]
	v_pk_mul_f32 v[22:23], v[22:23], v[248:249] op_sel_hi:[1,0]
	v_pk_mul_f32 v[24:25], v[24:25], v[248:249] op_sel_hi:[1,0]
	v_pk_mul_f32 v[26:27], v[26:27], v[248:249] op_sel_hi:[1,0]
	v_pk_mul_f32 v[28:29], v[28:29], v[248:249] op_sel_hi:[1,0]
	v_pk_mul_f32 v[30:31], v[30:31], v[248:249] op_sel_hi:[1,0]
	v_pk_mul_f32 v[32:33], v[32:33], v[248:249] op_sel_hi:[1,0]
	v_pk_mul_f32 v[34:35], v[34:35], v[248:249] op_sel_hi:[1,0]
	v_pk_mul_f32 v[36:37], v[36:37], v[248:249] op_sel_hi:[1,0]
	v_pk_mul_f32 v[38:39], v[38:39], v[248:249] op_sel_hi:[1,0]
	v_pk_mul_f32 v[40:41], v[40:41], v[248:249] op_sel_hi:[1,0]
	v_pk_mul_f32 v[42:43], v[42:43], v[248:249] op_sel_hi:[1,0]
	v_pk_mul_f32 v[44:45], v[44:45], v[248:249] op_sel_hi:[1,0]
	v_pk_mul_f32 v[46:47], v[46:47], v[248:249] op_sel_hi:[1,0]
	v_pk_mul_f32 v[48:49], v[48:49], v[248:249] op_sel_hi:[1,0]
	v_pk_mul_f32 v[50:51], v[50:51], v[248:249] op_sel_hi:[1,0]
	v_pk_mul_f32 v[52:53], v[52:53], v[248:249] op_sel_hi:[1,0]
	v_pk_mul_f32 v[54:55], v[54:55], v[248:249] op_sel_hi:[1,0]
	v_pk_mul_f32 v[56:57], v[56:57], v[248:249] op_sel_hi:[1,0]
	v_pk_mul_f32 v[58:59], v[58:59], v[248:249] op_sel_hi:[1,0]
	v_pk_mul_f32 v[60:61], v[60:61], v[248:249] op_sel_hi:[1,0]
	v_pk_mul_f32 v[62:63], v[62:63], v[248:249] op_sel_hi:[1,0]
	v_pk_mul_f32 v[64:65], v[64:65], v[248:249] op_sel_hi:[1,0]
.Lat_y_norescale:
	v_fma_f32 v66, v235, v66, -v195
	v_fma_f32 v67, v235, v67, -v195
	v_exp_f32_e32 v66, v66
	v_fma_f32 v68, v235, v68, -v195
	v_exp_f32_e32 v67, v67
	v_fma_f32 v69, v235, v69, -v195
	v_exp_f32_e32 v68, v68
	v_fma_f32 v70, v235, v70, -v195
	v_exp_f32_e32 v69, v69
	v_fma_f32 v71, v235, v71, -v195
	v_exp_f32_e32 v70, v70
	v_fma_f32 v72, v235, v72, -v195
	v_exp_f32_e32 v71, v71
	v_fma_f32 v73, v235, v73, -v195
	v_exp_f32_e32 v72, v72
	v_fma_f32 v74, v235, v74, -v195
	v_exp_f32_e32 v73, v73
	v_fma_f32 v75, v235, v75, -v195
	v_exp_f32_e32 v74, v74
	v_fma_f32 v76, v235, v76, -v195
	v_exp_f32_e32 v75, v75
	v_fma_f32 v77, v235, v77, -v195
	v_exp_f32_e32 v76, v76
	v_fma_f32 v78, v235, v78, -v195
	v_exp_f32_e32 v77, v77
	v_fma_f32 v79, v235, v79, -v195
	v_exp_f32_e32 v78, v78
	v_fma_f32 v80, v235, v80, -v195
	v_exp_f32_e32 v79, v79
	v_fma_f32 v81, v235, v81, -v195
	v_exp_f32_e32 v80, v80
	v_fma_f32 v82, v235, v82, -v195
	v_exp_f32_e32 v81, v81
	v_fma_f32 v83, v235, v83, -v195
	v_exp_f32_e32 v82, v82
	v_fma_f32 v84, v235, v84, -v195
	v_exp_f32_e32 v83, v83
	v_fma_f32 v85, v235, v85, -v195
	v_exp_f32_e32 v84, v84
	v_fma_f32 v86, v235, v86, -v195
	v_exp_f32_e32 v85, v85
	v_fma_f32 v87, v235, v87, -v195
	v_exp_f32_e32 v86, v86
	v_fma_f32 v88, v235, v88, -v195
	v_exp_f32_e32 v87, v87
	v_fma_f32 v89, v235, v89, -v195
	v_exp_f32_e32 v88, v88
	v_fma_f32 v90, v235, v90, -v195
	v_exp_f32_e32 v89, v89
	v_fma_f32 v91, v235, v91, -v195
	v_exp_f32_e32 v90, v90
	v_fma_f32 v92, v235, v92, -v195
	v_exp_f32_e32 v91, v91
	v_fma_f32 v93, v235, v93, -v195
	v_exp_f32_e32 v92, v92
	v_fma_f32 v94, v235, v94, -v195
	v_exp_f32_e32 v93, v93
	v_fma_f32 v95, v235, v95, -v195
	v_exp_f32_e32 v94, v94
	v_fma_f32 v96, v235, v96, -v195
	v_exp_f32_e32 v95, v95
	v_fma_f32 v97, v235, v97, -v195
	v_exp_f32_e32 v96, v96
	v_exp_f32_e32 v97, v97
	s_nop 0
	v_pk_add_f32 v[162:163], v[66:67], v[68:69]
	v_pk_add_f32 v[164:165], v[70:71], v[72:73]
	v_pk_add_f32 v[162:163], v[162:163], v[74:75]
	v_pk_add_f32 v[164:165], v[164:165], v[76:77]
	v_pk_add_f32 v[162:163], v[162:163], v[78:79]
	v_pk_add_f32 v[164:165], v[164:165], v[80:81]
	v_pk_add_f32 v[162:163], v[162:163], v[82:83]
	v_pk_add_f32 v[164:165], v[164:165], v[84:85]
	v_pk_add_f32 v[162:163], v[162:163], v[86:87]
	v_pk_add_f32 v[164:165], v[164:165], v[88:89]
	v_pk_add_f32 v[162:163], v[162:163], v[90:91]
	v_pk_add_f32 v[164:165], v[164:165], v[92:93]
	v_pk_add_f32 v[162:163], v[162:163], v[94:95]
	v_pk_add_f32 v[164:165], v[164:165], v[96:97]
	v_pk_add_f32 v[162:163], v[162:163], v[164:165]
	v_mov_b32_e32 v236, v195
	v_add_f32_e32 v0, v162, v163
	v_fma_f32 v237, v237, v248, v0
	v_cvt_pk_bf16_f32 v146, v66, v67
	v_cvt_pk_bf16_f32 v147, v68, v69
	v_cvt_pk_bf16_f32 v148, v70, v71
	v_cvt_pk_bf16_f32 v149, v72, v73
	v_cvt_pk_bf16_f32 v150, v74, v75
	v_cvt_pk_bf16_f32 v151, v76, v77
	v_cvt_pk_bf16_f32 v152, v78, v79
	v_cvt_pk_bf16_f32 v153, v80, v81
	v_cvt_pk_bf16_f32 v154, v82, v83
	v_cvt_pk_bf16_f32 v155, v84, v85
	v_cvt_pk_bf16_f32 v156, v86, v87
	v_cvt_pk_bf16_f32 v157, v88, v89
	v_cvt_pk_bf16_f32 v158, v90, v91
	v_cvt_pk_bf16_f32 v159, v92, v93
	v_cvt_pk_bf16_f32 v160, v94, v95
	v_cvt_pk_bf16_f32 v161, v96, v97
	s_branch .Lat_y_done
.Lat_x_noqk:
	s_waitcnt lgkmcnt(0)
	s_barrier
.Lat_y_done:
	s_barrier
	s_add_i32 s22, s22, 1
	s_add_i32 s24, s24, 1
	s_cmp_eq_u32 s24, 3
	s_cselect_b32 s24, 0, s24
	s_cmp_lt_u32 s22, s23
	s_cbranch_scc1 .Lat_loop
	s_add_i32 s65, s23, -1
	s_cmp_gt_i32 s65, s25
	s_cbranch_scc1 .Lat_f_nopv
	s_add_i32 s72, s24, 2
	s_cmp_ge_u32 s72, 3
	s_cbranch_scc0 .Lat_f_pvb
	s_sub_i32 s72, s72, 3

.Lat_f_nopv:
	s_cmp_lg_u32 s35, 0
	s_cbranch_scc1 .Lat_f_nobar
	s_barrier
.Lat_f_nobar:
	s_nop 15
	s_nop 7
	s_lshl_b32 s65, s34, 5
	s_cmp_lt_u32 s65, s28
	s_cbranch_scc0 .Lat_e_done
	ds_bpermute_b32 v0, v233, v237
	s_waitcnt lgkmcnt(0)
	v_add_f32_e32 v0, v0, v237
	v_rcp_f32_e32 v247, v0
	v_add_u32_e32 v0, s65, v240
	v_cmp_gt_u32_e32 vcc, s28, v0
	s_and_b64 vcc, vcc, s[2:3]
	s_and_saveexec_b64 s[4:5], vcc
	s_cbranch_execz .Lat_e_restore
	v_add_u32_e32 v0, s38, v234
	v_lshlrev_b32_e32 v0, 11, v0
	v_lshl_add_u32 v0, v241, 3, v0
	s_lshl_b32 s36, s30, 8
	s_add_u32 s36, s36, 0xc380000
	s_add_u32 s40, s48, s36
	s_addc_u32 s41, s49, 0
	global_load_dwordx2 v[162:163], v0, s[40:41] offset:0
	global_load_dwordx2 v[164:165], v0, s[40:41] offset:16
	global_load_dwordx2 v[166:167], v0, s[40:41] offset:32
	global_load_dwordx2 v[168:169], v0, s[40:41] offset:48
	global_load_dwordx2 v[170:171], v0, s[40:41] offset:64
	global_load_dwordx2 v[172:173], v0, s[40:41] offset:80
	global_load_dwordx2 v[174:175], v0, s[40:41] offset:96
	global_load_dwordx2 v[176:177], v0, s[40:41] offset:112
	global_load_dwordx2 v[178:179], v0, s[40:41] offset:128
	global_load_dwordx2 v[180:181], v0, s[40:41] offset:144
	global_load_dwordx2 v[182:183], v0, s[40:41] offset:160
	global_load_dwordx2 v[184:185], v0, s[40:41] offset:176
	global_load_dwordx2 v[186:187], v0, s[40:41] offset:192
	global_load_dwordx2 v[188:189], v0, s[40:41] offset:208
	global_load_dwordx2 v[190:191], v0, s[40:41] offset:224
	global_load_dwordx2 v[192:193], v0, s[40:41] offset:240
	s_waitcnt vmcnt(15)
	v_lshlrev_b32_e32 v194, 16, v162
	v_and_b32_e32 v195, 0xffff0000, v162
	v_lshlrev_b32_e32 v196, 16, v163
	v_and_b32_e32 v197, 0xffff0000, v163
	v_mul_f32_e32 v2, v2, v247
	v_mul_f32_e32 v3, v3, v247
	v_mul_f32_e32 v4, v4, v247
	v_mul_f32_e32 v5, v5, v247
	v_mul_f32_e32 v2, v2, v194
	v_mul_f32_e32 v3, v3, v195
	v_mul_f32_e32 v4, v4, v196
	v_mul_f32_e32 v5, v5, v197
	v_cvt_pk_bf16_f32 v66, v2, v3
	v_cvt_pk_bf16_f32 v67, v4, v5
	global_store_dwordx2 v0, v[66:67], s[40:41] offset:0
	s_waitcnt vmcnt(15)
	v_lshlrev_b32_e32 v194, 16, v164
	v_and_b32_e32 v195, 0xffff0000, v164
	v_lshlrev_b32_e32 v196, 16, v165
	v_and_b32_e32 v197, 0xffff0000, v165
	v_mul_f32_e32 v6, v6, v247
	v_mul_f32_e32 v7, v7, v247
	v_mul_f32_e32 v8, v8, v247
	v_mul_f32_e32 v9, v9, v247
	v_mul_f32_e32 v6, v6, v194
	v_mul_f32_e32 v7, v7, v195
	v_mul_f32_e32 v8, v8, v196
	v_mul_f32_e32 v9, v9, v197
	v_cvt_pk_bf16_f32 v68, v6, v7
	v_cvt_pk_bf16_f32 v69, v8, v9
	global_store_dwordx2 v0, v[68:69], s[40:41] offset:16
	s_waitcnt vmcnt(15)
	v_lshlrev_b32_e32 v194, 16, v166
	v_and_b32_e32 v195, 0xffff0000, v166
	v_lshlrev_b32_e32 v196, 16, v167
	v_and_b32_e32 v197, 0xffff0000, v167
	v_mul_f32_e32 v10, v10, v247
	v_mul_f32_e32 v11, v11, v247
	v_mul_f32_e32 v12, v12, v247
	v_mul_f32_e32 v13, v13, v247
	v_mul_f32_e32 v10, v10, v194
	v_mul_f32_e32 v11, v11, v195
	v_mul_f32_e32 v12, v12, v196
	v_mul_f32_e32 v13, v13, v197
	v_cvt_pk_bf16_f32 v70, v10, v11
	v_cvt_pk_bf16_f32 v71, v12, v13
	global_store_dwordx2 v0, v[70:71], s[40:41] offset:32
	s_waitcnt vmcnt(15)
	v_lshlrev_b32_e32 v194, 16, v168
	v_and_b32_e32 v195, 0xffff0000, v168
	v_lshlrev_b32_e32 v196, 16, v169
	v_and_b32_e32 v197, 0xffff0000, v169
	v_mul_f32_e32 v14, v14, v247
	v_mul_f32_e32 v15, v15, v247
	v_mul_f32_e32 v16, v16, v247
	v_mul_f32_e32 v17, v17, v247
	v_mul_f32_e32 v14, v14, v194
	v_mul_f32_e32 v15, v15, v195
	v_mul_f32_e32 v16, v16, v196
	v_mul_f32_e32 v17, v17, v197
	v_cvt_pk_bf16_f32 v72, v14, v15
	v_cvt_pk_bf16_f32 v73, v16, v17
	global_store_dwordx2 v0, v[72:73], s[40:41] offset:48
	s_waitcnt vmcnt(15)
	v_lshlrev_b32_e32 v194, 16, v170
	v_and_b32_e32 v195, 0xffff0000, v170
	v_lshlrev_b32_e32 v196, 16, v171
	v_and_b32_e32 v197, 0xffff0000, v171
	v_mul_f32_e32 v18, v18, v247
	v_mul_f32_e32 v19, v19, v247
	v_mul_f32_e32 v20, v20, v247
	v_mul_f32_e32 v21, v21, v247
	v_mul_f32_e32 v18, v18, v194
	v_mul_f32_e32 v19, v19, v195
	v_mul_f32_e32 v20, v20, v196
	v_mul_f32_e32 v21, v21, v197
	v_cvt_pk_bf16_f32 v74, v18, v19
	v_cvt_pk_bf16_f32 v75, v20, v21
	global_store_dwordx2 v0, v[74:75], s[40:41] offset:64
	s_waitcnt vmcnt(15)
	v_lshlrev_b32_e32 v194, 16, v172
	v_and_b32_e32 v195, 0xffff0000, v172
	v_lshlrev_b32_e32 v196, 16, v173
	v_and_b32_e32 v197, 0xffff0000, v173
	v_mul_f32_e32 v22, v22, v247
	v_mul_f32_e32 v23, v23, v247
	v_mul_f32_e32 v24, v24, v247
	v_mul_f32_e32 v25, v25, v247
	v_mul_f32_e32 v22, v22, v194
	v_mul_f32_e32 v23, v23, v195
	v_mul_f32_e32 v24, v24, v196
	v_mul_f32_e32 v25, v25, v197
	v_cvt_pk_bf16_f32 v76, v22, v23
	v_cvt_pk_bf16_f32 v77, v24, v25
	global_store_dwordx2 v0, v[76:77], s[40:41] offset:80
	s_waitcnt vmcnt(15)
	v_lshlrev_b32_e32 v194, 16, v174
	v_and_b32_e32 v195, 0xffff0000, v174
	v_lshlrev_b32_e32 v196, 16, v175
	v_and_b32_e32 v197, 0xffff0000, v175
	v_mul_f32_e32 v26, v26, v247
	v_mul_f32_e32 v27, v27, v247
	v_mul_f32_e32 v28, v28, v247
	v_mul_f32_e32 v29, v29, v247
	v_mul_f32_e32 v26, v26, v194
	v_mul_f32_e32 v27, v27, v195
	v_mul_f32_e32 v28, v28, v196
	v_mul_f32_e32 v29, v29, v197
	v_cvt_pk_bf16_f32 v78, v26, v27
	v_cvt_pk_bf16_f32 v79, v28, v29
	global_store_dwordx2 v0, v[78:79], s[40:41] offset:96
	s_waitcnt vmcnt(15)
	v_lshlrev_b32_e32 v194, 16, v176
	v_and_b32_e32 v195, 0xffff0000, v176
	v_lshlrev_b32_e32 v196, 16, v177
	v_and_b32_e32 v197, 0xffff0000, v177
	v_mul_f32_e32 v30, v30, v247
	v_mul_f32_e32 v31, v31, v247
	v_mul_f32_e32 v32, v32, v247
	v_mul_f32_e32 v33, v33, v247
	v_mul_f32_e32 v30, v30, v194
	v_mul_f32_e32 v31, v31, v195
	v_mul_f32_e32 v32, v32, v196
	v_mul_f32_e32 v33, v33, v197
	v_cvt_pk_bf16_f32 v80, v30, v31
	v_cvt_pk_bf16_f32 v81, v32, v33
	global_store_dwordx2 v0, v[80:81], s[40:41] offset:112
	s_waitcnt vmcnt(15)
	v_lshlrev_b32_e32 v194, 16, v178
	v_and_b32_e32 v195, 0xffff0000, v178
	v_lshlrev_b32_e32 v196, 16, v179
	v_and_b32_e32 v197, 0xffff0000, v179
	v_mul_f32_e32 v34, v34, v247
	v_mul_f32_e32 v35, v35, v247
	v_mul_f32_e32 v36, v36, v247
	v_mul_f32_e32 v37, v37, v247
	v_mul_f32_e32 v34, v34, v194
	v_mul_f32_e32 v35, v35, v195
	v_mul_f32_e32 v36, v36, v196
	v_mul_f32_e32 v37, v37, v197
	v_cvt_pk_bf16_f32 v82, v34, v35
	v_cvt_pk_bf16_f32 v83, v36, v37
	global_store_dwordx2 v0, v[82:83], s[40:41] offset:128
	s_waitcnt vmcnt(15)
	v_lshlrev_b32_e32 v194, 16, v180
	v_and_b32_e32 v195, 0xffff0000, v180
	v_lshlrev_b32_e32 v196, 16, v181
	v_and_b32_e32 v197, 0xffff0000, v181
	v_mul_f32_e32 v38, v38, v247
	v_mul_f32_e32 v39, v39, v247
	v_mul_f32_e32 v40, v40, v247
	v_mul_f32_e32 v41, v41, v247
	v_mul_f32_e32 v38, v38, v194
	v_mul_f32_e32 v39, v39, v195
	v_mul_f32_e32 v40, v40, v196
	v_mul_f32_e32 v41, v41, v197
	v_cvt_pk_bf16_f32 v84, v38, v39
	v_cvt_pk_bf16_f32 v85, v40, v41
	global_store_dwordx2 v0, v[84:85], s[40:41] offset:144
	s_waitcnt vmcnt(15)
	v_lshlrev_b32_e32 v194, 16, v182
	v_and_b32_e32 v195, 0xffff0000, v182
	v_lshlrev_b32_e32 v196, 16, v183
	v_and_b32_e32 v197, 0xffff0000, v183
	v_mul_f32_e32 v42, v42, v247
	v_mul_f32_e32 v43, v43, v247
	v_mul_f32_e32 v44, v44, v247
	v_mul_f32_e32 v45, v45, v247
	v_mul_f32_e32 v42, v42, v194
	v_mul_f32_e32 v43, v43, v195
	v_mul_f32_e32 v44, v44, v196
	v_mul_f32_e32 v45, v45, v197
	v_cvt_pk_bf16_f32 v86, v42, v43
	v_cvt_pk_bf16_f32 v87, v44, v45
	global_store_dwordx2 v0, v[86:87], s[40:41] offset:160
	s_waitcnt vmcnt(15)
	v_lshlrev_b32_e32 v194, 16, v184
	v_and_b32_e32 v195, 0xffff0000, v184
	v_lshlrev_b32_e32 v196, 16, v185
	v_and_b32_e32 v197, 0xffff0000, v185
	v_mul_f32_e32 v46, v46, v247
	v_mul_f32_e32 v47, v47, v247
	v_mul_f32_e32 v48, v48, v247
	v_mul_f32_e32 v49, v49, v247
	v_mul_f32_e32 v46, v46, v194
	v_mul_f32_e32 v47, v47, v195
	v_mul_f32_e32 v48, v48, v196
	v_mul_f32_e32 v49, v49, v197
	v_cvt_pk_bf16_f32 v88, v46, v47
	v_cvt_pk_bf16_f32 v89, v48, v49
	global_store_dwordx2 v0, v[88:89], s[40:41] offset:176
	s_waitcnt vmcnt(15)
	v_lshlrev_b32_e32 v194, 16, v186
	v_and_b32_e32 v195, 0xffff0000, v186
	v_lshlrev_b32_e32 v196, 16, v187
	v_and_b32_e32 v197, 0xffff0000, v187
	v_mul_f32_e32 v50, v50, v247
	v_mul_f32_e32 v51, v51, v247
	v_mul_f32_e32 v52, v52, v247
	v_mul_f32_e32 v53, v53, v247
	v_mul_f32_e32 v50, v50, v194
	v_mul_f32_e32 v51, v51, v195
	v_mul_f32_e32 v52, v52, v196
	v_mul_f32_e32 v53, v53, v197
	v_cvt_pk_bf16_f32 v90, v50, v51
	v_cvt_pk_bf16_f32 v91, v52, v53
	global_store_dwordx2 v0, v[90:91], s[40:41] offset:192
	s_waitcnt vmcnt(15)
	v_lshlrev_b32_e32 v194, 16, v188
	v_and_b32_e32 v195, 0xffff0000, v188
	v_lshlrev_b32_e32 v196, 16, v189
	v_and_b32_e32 v197, 0xffff0000, v189
	v_mul_f32_e32 v54, v54, v247
	v_mul_f32_e32 v55, v55, v247
	v_mul_f32_e32 v56, v56, v247
	v_mul_f32_e32 v57, v57, v247
	v_mul_f32_e32 v54, v54, v194
	v_mul_f32_e32 v55, v55, v195
	v_mul_f32_e32 v56, v56, v196
	v_mul_f32_e32 v57, v57, v197
	v_cvt_pk_bf16_f32 v92, v54, v55
	v_cvt_pk_bf16_f32 v93, v56, v57
	global_store_dwordx2 v0, v[92:93], s[40:41] offset:208
	s_waitcnt vmcnt(15)
	v_lshlrev_b32_e32 v194, 16, v190
	v_and_b32_e32 v195, 0xffff0000, v190
	v_lshlrev_b32_e32 v196, 16, v191
	v_and_b32_e32 v197, 0xffff0000, v191
	v_mul_f32_e32 v58, v58, v247
	v_mul_f32_e32 v59, v59, v247
	v_mul_f32_e32 v60, v60, v247
	v_mul_f32_e32 v61, v61, v247
	v_mul_f32_e32 v58, v58, v194
	v_mul_f32_e32 v59, v59, v195
	v_mul_f32_e32 v60, v60, v196
	v_mul_f32_e32 v61, v61, v197
	v_cvt_pk_bf16_f32 v94, v58, v59
	v_cvt_pk_bf16_f32 v95, v60, v61
	global_store_dwordx2 v0, v[94:95], s[40:41] offset:224
	s_waitcnt vmcnt(15)
	v_lshlrev_b32_e32 v194, 16, v192
	v_and_b32_e32 v195, 0xffff0000, v192
	v_lshlrev_b32_e32 v196, 16, v193
	v_and_b32_e32 v197, 0xffff0000, v193
	v_mul_f32_e32 v62, v62, v247
	v_mul_f32_e32 v63, v63, v247
	v_mul_f32_e32 v64, v64, v247
	v_mul_f32_e32 v65, v65, v247
	v_mul_f32_e32 v62, v62, v194
	v_mul_f32_e32 v63, v63, v195
	v_mul_f32_e32 v64, v64, v196
	v_mul_f32_e32 v65, v65, v197
	v_cvt_pk_bf16_f32 v96, v62, v63
	v_cvt_pk_bf16_f32 v97, v64, v65
	global_store_dwordx2 v0, v[96:97], s[40:41] offset:240

.Lat_e_done:
	s_barrier
	s_add_i32 s26, s26, 1
	s_cmp_eq_u32 s26, 3
	s_cbranch_scc1 .Lat_all_done
	s_cmp_lt_u32 s26, 2
	s_cbranch_scc1 .Lat_item
	s_cmp_eq_u32 s31, 0
	s_cbranch_scc1 .Lat_item
.Lat_all_done:
	s_waitcnt vmcnt(0)
	s_branch .LBB0_384
